# out-projection phases: per-XCD start delay span 40 -> 70 us (the baseline's own stagger constant)
# speedup vs baseline: 1.0001x; 1.0001x over previous
.LBB0_561:
	s_abs_i32 s3, s10
	v_cvt_f32_u32_e32 v0, s3
	s_sub_i32 s11, 0, s3
	v_rcp_iflag_f32_e32 v0, v0
	s_nop 0
	v_mul_f32_e32 v0, 0x4f7ffffe, v0
	v_cvt_u32_f32_e32 v0, v0
	s_nop 0
	v_readfirstlane_b32 s14, v0
	s_mul_i32 s11, s11, s14
	s_mul_hi_u32 s11, s14, s11
	s_add_i32 s14, s14, s11
	s_mul_hi_u32 s11, s14, 0x440
	s_mul_i32 s11, s11, s3
	s_sub_i32 s11, 0x440, s11
	s_sub_i32 s14, s11, s3
	s_cmp_ge_u32 s11, s3
	s_cselect_b32 s11, s14, s11
	s_sub_i32 s14, s11, s3
	s_cmp_ge_u32 s11, s3
	s_cselect_b32 s3, s14, s11
	s_cmp_eq_u32 s3, 0
	s_cbranch_scc1 .LBB0_559
	s_ashr_i32 s11, s10, 3
	s_abs_i32 s10, s11
	v_cvt_f32_u32_e32 v0, s10
	s_sub_i32 s16, 0, s10
	s_abs_i32 s14, s3
	s_xor_b32 s15, s3, s11
	v_rcp_iflag_f32_e32 v0, v0
	s_ashr_i32 s15, s15, 31
	v_mul_f32_e32 v0, 0x4f7ffffe, v0
	v_cvt_u32_f32_e32 v0, v0
	s_nop 0
	v_readfirstlane_b32 s17, v0
	s_mul_i32 s16, s16, s17
	s_mul_hi_u32 s16, s17, s16
	s_add_i32 s17, s17, s16
	s_mul_hi_u32 s16, s14, s17
	s_mul_i32 s17, s16, s10
	s_sub_i32 s14, s14, s17
	s_add_i32 s18, s16, 1
	s_sub_i32 s17, s14, s10
	s_cmp_ge_u32 s14, s10
	s_cselect_b32 s16, s18, s16
	s_cselect_b32 s14, s17, s14
	s_add_i32 s17, s16, 1
	s_cmp_ge_u32 s14, s10
	s_cselect_b32 s10, s17, s16
	s_xor_b32 s10, s10, s15
	s_sub_i32 s10, s10, s15
	s_mul_i32 s11, s10, s11
	s_sub_i32 s3, s3, s11
	s_cmp_lg_u32 s3, 0
	s_cbranch_scc1 .LBB0_559
	s_and_b32 s2, s2, 7
	s_cmp_lt_i32 s2, s10
	s_cbranch_scc1 .LBB0_559
	s_sub_i32 s2, s2, s10
	v_cvt_f32_i32_e32 v0, s2
	s_sub_i32 s2, 8, s10
	v_cvt_f32_u32_e32 v1, s2
	v_mul_f32_e32 v0, 0x45dac000, v0
	v_div_scale_f32 v2, s[2:3], v1, v1, v0
	v_rcp_f32_e32 v3, v2
	v_div_scale_f32 v4, vcc, v0, v1, v0
	s_memrealtime s[2:3]
	v_fma_f32 v5, -v2, v3, 1.0
	v_fmac_f32_e32 v3, v5, v3
	v_mul_f32_e32 v5, v4, v3
	v_fma_f32 v6, -v2, v5, v4
	v_fmac_f32_e32 v5, v6, v3
	v_fma_f32 v2, -v2, v5, v4
	v_div_fmas_f32 v2, v2, v3, v5
	v_div_fixup_f32 v0, v2, v1, v0
	v_trunc_f32_e32 v0, v0
	v_mul_f32_e32 v1, 0x2f800000, v0
	v_floor_f32_e32 v1, v1
	v_fmac_f32_e32 v0, 0xcf800000, v1
	v_cvt_u32_f32_e32 v0, v0
	v_cvt_u32_f32_e32 v1, v1
	s_memrealtime s[10:11]
	s_waitcnt lgkmcnt(0)
	v_lshl_add_u64 v[0:1], s[2:3], 0, v[0:1]
	v_cmp_ge_u64_e32 vcc, s[10:11], v[0:1]
	s_cbranch_vccnz .LBB0_559

.LBB0_931:
	s_abs_i32 s3, s8
	v_cvt_f32_u32_e32 v0, s3
	s_sub_i32 s9, 0, s3
	v_rcp_iflag_f32_e32 v0, v0
	s_nop 0
	v_mul_f32_e32 v0, 0x4f7ffffe, v0
	v_cvt_u32_f32_e32 v0, v0
	s_nop 0
	v_readfirstlane_b32 s10, v0
	s_mul_i32 s9, s9, s10
	s_mul_hi_u32 s9, s10, s9
	s_add_i32 s10, s10, s9
	s_mul_hi_u32 s9, s10, 0x440
	s_mul_i32 s9, s9, s3
	s_sub_i32 s9, 0x440, s9
	s_sub_i32 s10, s9, s3
	s_cmp_ge_u32 s9, s3
	s_cselect_b32 s9, s10, s9
	s_sub_i32 s10, s9, s3
	s_cmp_ge_u32 s9, s3
	s_cselect_b32 s3, s10, s9
	s_cmp_eq_u32 s3, 0
	s_cbranch_scc1 .LBB0_929
	s_ashr_i32 s9, s8, 3
	s_abs_i32 s8, s9
	v_cvt_f32_u32_e32 v0, s8
	s_sub_i32 s14, 0, s8
	s_abs_i32 s10, s3
	s_xor_b32 s11, s3, s9
	v_rcp_iflag_f32_e32 v0, v0
	s_ashr_i32 s11, s11, 31
	v_mul_f32_e32 v0, 0x4f7ffffe, v0
	v_cvt_u32_f32_e32 v0, v0
	s_nop 0
	v_readfirstlane_b32 s15, v0
	s_mul_i32 s14, s14, s15
	s_mul_hi_u32 s14, s15, s14
	s_add_i32 s15, s15, s14
	s_mul_hi_u32 s14, s10, s15
	s_mul_i32 s15, s14, s8
	s_sub_i32 s10, s10, s15
	s_add_i32 s16, s14, 1
	s_sub_i32 s15, s10, s8
	s_cmp_ge_u32 s10, s8
	s_cselect_b32 s14, s16, s14
	s_cselect_b32 s10, s15, s10
	s_add_i32 s15, s14, 1
	s_cmp_ge_u32 s10, s8
	s_cselect_b32 s8, s15, s14
	s_xor_b32 s8, s8, s11
	s_sub_i32 s8, s8, s11
	s_mul_i32 s9, s8, s9
	s_sub_i32 s3, s3, s9
	s_cmp_lg_u32 s3, 0
	s_cbranch_scc1 .LBB0_929
	s_and_b32 s2, s2, 7
	s_cmp_lt_i32 s2, s8
	s_cbranch_scc1 .LBB0_929
	s_sub_i32 s2, s2, s8
	v_cvt_f32_i32_e32 v0, s2
	s_sub_i32 s2, 8, s8
	v_cvt_f32_u32_e32 v1, s2
	v_mul_f32_e32 v0, 0x45dac000, v0
	v_div_scale_f32 v2, s[2:3], v1, v1, v0
	v_rcp_f32_e32 v3, v2
	v_div_scale_f32 v4, vcc, v0, v1, v0
	s_memrealtime s[2:3]
	v_fma_f32 v5, -v2, v3, 1.0
	v_fmac_f32_e32 v3, v5, v3
	v_mul_f32_e32 v5, v4, v3
	v_fma_f32 v6, -v2, v5, v4
	v_fmac_f32_e32 v5, v6, v3
	v_fma_f32 v2, -v2, v5, v4
	v_div_fmas_f32 v2, v2, v3, v5
	v_div_fixup_f32 v0, v2, v1, v0
	v_trunc_f32_e32 v0, v0
	v_mul_f32_e32 v1, 0x2f800000, v0
	v_floor_f32_e32 v1, v1
	v_fmac_f32_e32 v0, 0xcf800000, v1
	v_cvt_u32_f32_e32 v0, v0
	v_cvt_u32_f32_e32 v1, v1
	s_memrealtime s[8:9]
	s_waitcnt lgkmcnt(0)
	v_lshl_add_u64 v[0:1], s[2:3], 0, v[0:1]
	v_cmp_ge_u64_e32 vcc, s[8:9], v[0:1]
	s_cbranch_vccnz .LBB0_929
